# attention loop: K/V tile written to LDS at iteration start, global loads in flight a full iteration; deeper exp->cvt software pipeline
# baseline (speedup 1.0000x reference)
.LBB0_1012:
	s_ashr_i32 s39, s0, 7
	s_lshl_b32 s4, s0, 9
	s_bfe_u32 s1, s0, 0x40003
	s_and_b32 s40, s4, 0xe00
	s_lshl_b32 s4, s39, 4
	s_or_b32 s4, s4, s1
	s_add_i32 s40, s40, s38
	s_ashr_i32 s5, s4, 31
	s_lshr_b32 s6, s0, 3
	s_lshl_b64 s[4:5], s[4:5], 12
	s_ashr_i32 s7, s40, 31
	s_add_u32 s4, s4, s40
	s_addc_u32 s5, s5, s7
	v_mov_b32_e32 v1, s5
	v_or_b32_e32 v0, s4, v202
	s_bfe_u32 s4, s6, 0x20002
	s_lshl_b32 s5, s39, 2
	s_or_b32 s4, s4, s5
	v_lshlrev_b64 v[0:1], 7, v[0:1]
	s_ashr_i32 s5, s4, 31
	v_lshl_add_u64 v[2:3], v[204:205], 0, v[0:1]
	v_or_b32_e32 v0, 0x1000, v0
	s_lshl_b64 s[4:5], s[4:5], 19
	v_lshl_add_u64 v[0:1], v[204:205], 0, v[0:1]
	v_lshl_add_u64 v[212:213], v[208:209], 0, s[4:5]
	global_load_dwordx4 v[130:133], v[2:3], off
	global_load_dwordx4 v[134:137], v[2:3], off offset:32
	global_load_dwordx4 v[138:141], v[2:3], off offset:64
	global_load_dwordx4 v[142:145], v[2:3], off offset:96
	global_load_dwordx4 v[146:149], v[0:1], off
	global_load_dwordx4 v[150:153], v[0:1], off offset:32
	global_load_dwordx4 v[154:157], v[0:1], off offset:64
	global_load_dwordx4 v[158:161], v[0:1], off offset:96
	v_lshl_add_u64 v[214:215], v[210:211], 0, s[4:5]
	global_load_dwordx4 v[0:3], v[212:213], off
	global_load_dwordx4 v[4:7], v[214:215], off
	v_mov_b32_e32 v82, 0xf149f2ca
	s_mov_b32 s4, 0
	s_movk_i32 s42, 0x6c00
	s_movk_i32 s41, 0x4800
	s_mov_b32 s5, 0x9000
	v_mov_b32_e32 v162, 0
	v_mov_b32_e32 v163, 0
	v_mov_b32_e32 v164, 0
	v_mov_b32_e32 v165, 0
	v_mov_b32_e32 v174, 0
	v_mov_b32_e32 v175, 0
	v_mov_b32_e32 v176, 0
	v_mov_b32_e32 v177, 0
	v_mov_b32_e32 v166, 0
	v_mov_b32_e32 v167, 0
	v_mov_b32_e32 v168, 0
	v_mov_b32_e32 v169, 0
	v_mov_b32_e32 v170, 0
	v_mov_b32_e32 v171, 0
	v_mov_b32_e32 v172, 0
	v_mov_b32_e32 v173, 0
	v_mov_b32_e32 v83, v82
	v_mov_b32_e32 v84, v82
	v_mov_b32_e32 v85, v82
	v_mov_b32_e32 v86, v82
	v_mov_b32_e32 v87, v82
	v_mov_b32_e32 v88, v82
	v_mov_b32_e32 v89, v82
	v_mov_b32_e32 v90, v82
	v_mov_b32_e32 v91, v82
	v_mov_b32_e32 v92, v82
	v_mov_b32_e32 v93, v82
	v_mov_b32_e32 v94, v82
	v_mov_b32_e32 v95, v82
	v_mov_b32_e32 v96, v82
	v_mov_b32_e32 v97, v82
	v_mov_b32_e32 v66, v82
	v_mov_b32_e32 v67, v82
	v_mov_b32_e32 v68, v82
	v_mov_b32_e32 v69, v82
	v_mov_b32_e32 v70, v82
	v_mov_b32_e32 v71, v82
	v_mov_b32_e32 v72, v82
	v_mov_b32_e32 v73, v82
	v_mov_b32_e32 v74, v82
	v_mov_b32_e32 v75, v82
	v_mov_b32_e32 v76, v82
	v_mov_b32_e32 v77, v82
	v_mov_b32_e32 v78, v82
	v_mov_b32_e32 v79, v82
	v_mov_b32_e32 v80, v82
	v_mov_b32_e32 v81, v82
	s_waitcnt vmcnt(1)
	ds_write_b128 v203, v[0:3]
	s_waitcnt vmcnt(0)
	ds_write_b128 v203, v[4:7] offset:18432
	v_mov_b32_e32 v0, 0
	v_mov_b32_e32 v1, v0
	v_mov_b32_e32 v2, v0
	v_mov_b32_e32 v3, v0
	v_mov_b32_e32 v4, v0
	v_mov_b32_e32 v5, v0
	v_mov_b32_e32 v6, v0
	v_mov_b32_e32 v7, v0
	v_mov_b32_e32 v8, v0
	v_mov_b32_e32 v9, v0
	v_mov_b32_e32 v10, v0
	v_mov_b32_e32 v11, v0
	v_mov_b32_e32 v12, v0
	v_mov_b32_e32 v13, v0
	v_mov_b32_e32 v14, v0
	v_mov_b32_e32 v15, v0
	v_mov_b32_e32 v16, v0
	v_mov_b32_e32 v17, v0
	v_mov_b32_e32 v18, v0
	v_mov_b32_e32 v19, v0
	v_mov_b32_e32 v20, v0
	v_mov_b32_e32 v21, v0
	v_mov_b32_e32 v22, v0
	v_mov_b32_e32 v23, v0
	v_mov_b32_e32 v24, v0
	v_mov_b32_e32 v25, v0
	v_mov_b32_e32 v26, v0
	v_mov_b32_e32 v27, v0
	v_mov_b32_e32 v28, v0
	v_mov_b32_e32 v29, v0
	v_mov_b32_e32 v30, v0
	v_mov_b32_e32 v31, v0
	v_mov_b32_e32 v34, v0
	v_mov_b32_e32 v35, v0
	v_mov_b32_e32 v36, v0
	v_mov_b32_e32 v37, v0
	v_mov_b32_e32 v38, v0
	v_mov_b32_e32 v39, v0
	v_mov_b32_e32 v40, v0
	v_mov_b32_e32 v41, v0
	v_mov_b32_e32 v42, v0
	v_mov_b32_e32 v43, v0
	v_mov_b32_e32 v44, v0
	v_mov_b32_e32 v45, v0
	v_mov_b32_e32 v46, v0
	v_mov_b32_e32 v47, v0
	v_mov_b32_e32 v48, v0
	v_mov_b32_e32 v49, v0
	v_mov_b32_e32 v50, v0
	v_mov_b32_e32 v51, v0
	v_mov_b32_e32 v52, v0
	v_mov_b32_e32 v53, v0
	v_mov_b32_e32 v54, v0
	v_mov_b32_e32 v55, v0
	v_mov_b32_e32 v56, v0
	v_mov_b32_e32 v57, v0
	v_mov_b32_e32 v58, v0
	v_mov_b32_e32 v59, v0
	v_mov_b32_e32 v60, v0
	v_mov_b32_e32 v61, v0
	v_mov_b32_e32 v62, v0
	v_mov_b32_e32 v63, v0
	v_mov_b32_e32 v64, v0
	v_mov_b32_e32 v65, v0
	v_mov_b32_e32 v216, v0
	v_mov_b32_e32 v217, v0
	s_waitcnt lgkmcnt(0)
	s_barrier
	v_mov_b32_e32 v234, v245
	v_add_u32_e32 v235, s5, v32
	s_mov_b64 s[6:7], 0x2000
	v_lshl_add_u64 v[182:183], v[212:213], 0, s[6:7]
	ds_read_b128 v[226:229], v235
	ds_read_b128 v[230:233], v235 offset:4608
	global_load_dwordx4 v[182:185], v[182:183], off
	global_load_dwordx4 v[178:181], v[214:215], off offset:128
.LBB0_1013:
	s_waitcnt lgkmcnt(1)
	v_mfma_f32_32x32x16_bf16 v[50:65], v[226:229], v[170:173], v[50:65]
	s_add_i32 s44, s4, 1
	s_and_b32 s43, s44, 1
	s_mul_i32 s43, s43, 0x2400
	v_add_u32_e32 v199, s42, v203
	v_add_u32_e32 v198, s43, v203
	s_add_i32 s16, s4, 2
	s_min_u32 s16, s16, 63
	s_waitcnt vmcnt(0)
	ds_write_b128 v199, v[178:181]
	ds_write_b128 v198, v[182:185]
	s_lshl_b64 s[6:7], s[16:17], 13
	ds_read_b128 v[246:249], v235 offset:32
	v_lshl_add_u64 v[182:183], v[212:213], 0, s[6:7]
	s_lshl_b64 s[6:7], s[16:17], 7
	global_load_dwordx4 v[182:185], v[182:183], off
	v_lshl_add_u64 v[178:179], v[214:215], 0, s[6:7]
	s_nop 0
	global_load_dwordx4 v[178:181], v[178:179], off
	v_mfma_f32_32x32x16_bf16 v[16:31], v[226:229], v[174:177], v[16:31]
	v_exp_f32_e32 v82, v82
	v_exp_f32_e32 v83, v83
	v_exp_f32_e32 v84, v84
	v_exp_f32_e32 v85, v85
	v_exp_f32_e32 v86, v86
	s_waitcnt lgkmcnt(3)
	v_mfma_f32_32x32x16_bf16 v[34:49], v[230:233], v[170:173], v[34:49]
	v_exp_f32_e32 v87, v87
	v_exp_f32_e32 v88, v88
	v_exp_f32_e32 v89, v89
	v_cvt_pk_bf16_f32 v186, v82, v83
	v_add_f32_e32 v82, v82, v83
	ds_read_b128 v[226:229], v235 offset:4640
	v_mfma_f32_32x32x16_bf16 v[0:15], v[230:233], v[174:177], v[0:15]
	v_exp_f32_e32 v90, v90
	v_exp_f32_e32 v91, v91
	v_cvt_pk_bf16_f32 v187, v84, v85
	v_add_f32_e32 v84, v84, v85
	v_add_f32_e32 v217, v217, v82
	v_exp_f32_e32 v92, v92
	s_waitcnt lgkmcnt(1)
	v_mfma_f32_32x32x16_bf16 v[50:65], v[246:249], v[166:169], v[50:65]
	v_exp_f32_e32 v93, v93
	v_cvt_pk_bf16_f32 v188, v86, v87
	v_add_f32_e32 v86, v86, v87
	v_add_f32_e32 v217, v217, v84
	v_exp_f32_e32 v94, v94
	ds_read_b128 v[230:233], v234
	v_mfma_f32_32x32x16_bf16 v[16:31], v[246:249], v[162:165], v[16:31]
	v_exp_f32_e32 v95, v95
	v_cvt_pk_bf16_f32 v189, v88, v89
	v_add_f32_e32 v88, v88, v89
	v_add_f32_e32 v217, v217, v86
	v_exp_f32_e32 v96, v96
	s_waitcnt lgkmcnt(1)
	v_mfma_f32_32x32x16_bf16 v[34:49], v[226:229], v[166:169], v[34:49]
	v_exp_f32_e32 v97, v97
	v_cvt_pk_bf16_f32 v190, v90, v91
	v_add_f32_e32 v90, v90, v91
	v_add_f32_e32 v217, v217, v88
	v_exp_f32_e32 v66, v66
	v_exp_f32_e32 v67, v67
	ds_read_b128 v[246:249], v234 offset:32
	v_mfma_f32_32x32x16_bf16 v[0:15], v[226:229], v[162:165], v[0:15]
	v_cvt_pk_bf16_f32 v191, v92, v93
	v_add_f32_e32 v92, v92, v93
	v_add_f32_e32 v217, v217, v90
	v_exp_f32_e32 v68, v68
	v_exp_f32_e32 v69, v69
	s_waitcnt lgkmcnt(1)
	v_mfma_f32_32x32x16_bf16 v[114:129], v[230:233], v[130:133], 0
	v_cvt_pk_bf16_f32 v192, v94, v95
	v_add_f32_e32 v94, v94, v95
	v_add_f32_e32 v217, v217, v92
	v_exp_f32_e32 v70, v70
	v_exp_f32_e32 v71, v71
	ds_read_b128 v[226:229], v234 offset:64
	v_mfma_f32_32x32x16_bf16 v[98:113], v[230:233], v[146:149], 0
	v_cvt_pk_bf16_f32 v193, v96, v97
	v_add_f32_e32 v96, v96, v97
	v_add_f32_e32 v217, v217, v94
	v_exp_f32_e32 v72, v72
	v_exp_f32_e32 v73, v73
	v_cvt_pk_bf16_f32 v218, v66, v67
	s_waitcnt lgkmcnt(1)
	v_mfma_f32_32x32x16_bf16 v[114:129], v[246:249], v[134:137], v[114:129]
	v_add_f32_e32 v66, v66, v67
	v_add_f32_e32 v217, v217, v96
	v_exp_f32_e32 v74, v74
	v_exp_f32_e32 v75, v75
	v_cvt_pk_bf16_f32 v219, v68, v69
	ds_read_b128 v[230:233], v234 offset:96
	v_mfma_f32_32x32x16_bf16 v[98:113], v[246:249], v[150:153], v[98:113]
	v_add_f32_e32 v68, v68, v69
	v_add_f32_e32 v216, v216, v66
	v_exp_f32_e32 v76, v76
	v_exp_f32_e32 v77, v77
	v_cvt_pk_bf16_f32 v220, v70, v71
	s_waitcnt lgkmcnt(1)
	v_mfma_f32_32x32x16_bf16 v[114:129], v[226:229], v[138:141], v[114:129]
	v_add_f32_e32 v70, v70, v71
	v_add_f32_e32 v216, v216, v68
	v_exp_f32_e32 v78, v78
	v_exp_f32_e32 v79, v79
	v_cvt_pk_bf16_f32 v221, v72, v73
	v_add_f32_e32 v72, v72, v73
	v_mfma_f32_32x32x16_bf16 v[98:113], v[226:229], v[154:157], v[98:113]
	v_add_f32_e32 v216, v216, v70
	v_exp_f32_e32 v80, v80
	v_exp_f32_e32 v81, v81
	v_cvt_pk_bf16_f32 v222, v74, v75
	v_add_f32_e32 v74, v74, v75
	ds_read_b128 v[226:229], v235 offset:64
	s_waitcnt lgkmcnt(1)
	v_mfma_f32_32x32x16_bf16 v[114:129], v[230:233], v[142:145], v[114:129]
	v_add_f32_e32 v216, v216, v72
	v_cvt_pk_bf16_f32 v223, v76, v77
	v_add_f32_e32 v76, v76, v77
	v_add_f32_e32 v216, v216, v74
	v_cvt_pk_bf16_f32 v224, v78, v79
	v_mfma_f32_32x32x16_bf16 v[98:113], v[230:233], v[158:161], v[98:113]
	v_add_f32_e32 v78, v78, v79
	v_add_f32_e32 v216, v216, v76
	v_cvt_pk_bf16_f32 v225, v80, v81
	v_add_f32_e32 v80, v80, v81
	v_add_f32_e32 v216, v216, v78
	v_add_f32_e32 v216, v216, v80
	ds_read_b128 v[230:233], v235 offset:4672
	s_waitcnt lgkmcnt(1)
	v_mfma_f32_32x32x16_bf16 v[50:65], v[226:229], v[186:189], v[50:65]
	ds_read_b128 v[246:249], v235 offset:96
	v_mfma_f32_32x32x16_bf16 v[16:31], v[226:229], v[218:221], v[16:31]
	v_exp_f32_e32 v114, v114
	v_exp_f32_e32 v115, v115
	v_exp_f32_e32 v116, v116
	v_exp_f32_e32 v117, v117
	v_exp_f32_e32 v118, v118
	s_waitcnt lgkmcnt(1)
	v_mfma_f32_32x32x16_bf16 v[34:49], v[230:233], v[186:189], v[34:49]
	v_exp_f32_e32 v119, v119
	v_exp_f32_e32 v120, v120
	v_exp_f32_e32 v121, v121
	v_cvt_pk_bf16_f32 v170, v114, v115
	v_add_f32_e32 v114, v114, v115
	ds_read_b128 v[226:229], v235 offset:4704
	v_mfma_f32_32x32x16_bf16 v[0:15], v[230:233], v[218:221], v[0:15]
	v_exp_f32_e32 v122, v122
	v_exp_f32_e32 v123, v123
	v_cvt_pk_bf16_f32 v171, v116, v117
	v_add_f32_e32 v116, v116, v117
	v_add_f32_e32 v217, v217, v114
	v_exp_f32_e32 v124, v124
	v_add_u32_e32 v235, s41, v32
	s_waitcnt lgkmcnt(1)
	v_mfma_f32_32x32x16_bf16 v[50:65], v[246:249], v[190:193], v[50:65]
	v_exp_f32_e32 v125, v125
	v_cvt_pk_bf16_f32 v172, v118, v119
	v_add_f32_e32 v118, v118, v119
	v_add_f32_e32 v217, v217, v116
	v_exp_f32_e32 v126, v126
	ds_read_b128 v[230:233], v234 offset:4608
	v_mfma_f32_32x32x16_bf16 v[16:31], v[246:249], v[222:225], v[16:31]
	v_exp_f32_e32 v127, v127
	v_cvt_pk_bf16_f32 v173, v120, v121
	v_add_f32_e32 v120, v120, v121
	v_add_f32_e32 v217, v217, v118
	v_exp_f32_e32 v128, v128
	s_waitcnt lgkmcnt(1)
	v_mfma_f32_32x32x16_bf16 v[34:49], v[226:229], v[190:193], v[34:49]
	v_exp_f32_e32 v129, v129
	v_cvt_pk_bf16_f32 v166, v122, v123
	v_add_f32_e32 v122, v122, v123
	v_add_f32_e32 v217, v217, v120
	v_exp_f32_e32 v98, v98
	v_exp_f32_e32 v99, v99
	ds_read_b128 v[246:249], v234 offset:4640
	v_mfma_f32_32x32x16_bf16 v[0:15], v[226:229], v[222:225], v[0:15]
	v_cvt_pk_bf16_f32 v167, v124, v125
	v_add_f32_e32 v124, v124, v125
	v_add_f32_e32 v217, v217, v122
	v_exp_f32_e32 v100, v100
	v_exp_f32_e32 v101, v101
	s_waitcnt lgkmcnt(1)
	v_mfma_f32_32x32x16_bf16 v[82:97], v[230:233], v[130:133], 0
	v_cvt_pk_bf16_f32 v168, v126, v127
	v_add_f32_e32 v126, v126, v127
	v_add_f32_e32 v217, v217, v124
	v_exp_f32_e32 v102, v102
	v_exp_f32_e32 v103, v103
	ds_read_b128 v[226:229], v234 offset:4672
	v_mfma_f32_32x32x16_bf16 v[66:81], v[230:233], v[146:149], 0
	v_cvt_pk_bf16_f32 v169, v128, v129
	v_add_f32_e32 v128, v128, v129
	v_add_f32_e32 v217, v217, v126
	v_exp_f32_e32 v104, v104
	v_exp_f32_e32 v105, v105
	v_cvt_pk_bf16_f32 v174, v98, v99
	s_waitcnt lgkmcnt(1)
	v_mfma_f32_32x32x16_bf16 v[82:97], v[246:249], v[134:137], v[82:97]
	v_add_f32_e32 v98, v98, v99
	v_add_f32_e32 v217, v217, v128
	v_exp_f32_e32 v106, v106
	v_exp_f32_e32 v107, v107
	v_cvt_pk_bf16_f32 v175, v100, v101
	ds_read_b128 v[230:233], v234 offset:4704
	v_mfma_f32_32x32x16_bf16 v[66:81], v[246:249], v[150:153], v[66:81]
	v_add_f32_e32 v100, v100, v101
	v_add_f32_e32 v216, v216, v98
	v_exp_f32_e32 v108, v108
	v_exp_f32_e32 v109, v109
	v_cvt_pk_bf16_f32 v176, v102, v103
	v_add_u32_e32 v234, s43, v245
	s_waitcnt lgkmcnt(1)
	v_mfma_f32_32x32x16_bf16 v[82:97], v[226:229], v[138:141], v[82:97]
	v_add_f32_e32 v102, v102, v103
	v_add_f32_e32 v216, v216, v100
	v_exp_f32_e32 v110, v110
	v_exp_f32_e32 v111, v111
	v_cvt_pk_bf16_f32 v177, v104, v105
	v_add_f32_e32 v104, v104, v105
	v_mfma_f32_32x32x16_bf16 v[66:81], v[226:229], v[154:157], v[66:81]
	v_add_f32_e32 v216, v216, v102
	v_exp_f32_e32 v112, v112
	v_exp_f32_e32 v113, v113
	v_cvt_pk_bf16_f32 v162, v106, v107
	v_add_f32_e32 v106, v106, v107
	ds_read_b128 v[226:229], v235
	s_waitcnt lgkmcnt(1)
	v_mfma_f32_32x32x16_bf16 v[82:97], v[230:233], v[142:145], v[82:97]
	v_add_f32_e32 v216, v216, v104
	v_cvt_pk_bf16_f32 v163, v108, v109
	v_add_f32_e32 v108, v108, v109
	v_add_f32_e32 v216, v216, v106
	v_cvt_pk_bf16_f32 v164, v110, v111
	v_mfma_f32_32x32x16_bf16 v[66:81], v[230:233], v[158:161], v[66:81]
	v_add_f32_e32 v110, v110, v111
	v_add_f32_e32 v216, v216, v108
	v_cvt_pk_bf16_f32 v165, v112, v113
	v_add_f32_e32 v112, v112, v113
	v_add_f32_e32 v216, v216, v110
	v_add_f32_e32 v216, v216, v112
	ds_read_b128 v[230:233], v235 offset:4608
	s_mov_b32 s6, s5
	s_mov_b32 s5, s41
	s_mov_b32 s41, s42
	s_mov_b32 s42, s6
	s_mov_b32 s4, s44
	s_cmp_eq_u32 s44, 64
	s_barrier
	s_cbranch_scc0 .LBB0_1013
	s_waitcnt vmcnt(0)
	v_exp_f32_e32 v82, v82
	v_exp_f32_e32 v83, v83
	v_exp_f32_e32 v84, v84
	v_exp_f32_e32 v85, v85
	v_add_f32_e32 v98, 0, v82
	v_exp_f32_e32 v99, v86
	v_add_f32_e32 v98, v83, v98
	v_add_f32_e32 v98, v84, v98
	v_add_f32_e32 v98, v85, v98
	v_add_f32_e32 v86, v99, v98
	v_exp_f32_e32 v98, v87
	v_exp_f32_e32 v100, v88
	v_exp_f32_e32 v89, v89
	v_exp_f32_e32 v101, v90
	v_add_f32_e32 v86, v98, v86
	v_exp_f32_e32 v91, v91
	v_add_f32_e32 v86, v100, v86
	v_exp_f32_e32 v92, v92
	v_add_f32_e32 v86, v89, v86
	v_exp_f32_e32 v93, v93
	v_add_f32_e32 v86, v101, v86
	v_exp_f32_e32 v94, v94
	v_add_f32_e32 v86, v91, v86
	v_exp_f32_e32 v95, v95
	v_add_f32_e32 v86, v92, v86
	v_exp_f32_e32 v96, v96
	v_add_f32_e32 v86, v93, v86
	v_exp_f32_e32 v97, v97
	v_add_f32_e32 v86, v94, v86
	v_exp_f32_e32 v66, v66
	v_add_f32_e32 v86, v95, v86
	v_exp_f32_e32 v67, v67
	v_add_f32_e32 v86, v96, v86
	v_exp_f32_e32 v68, v68
	v_add_f32_e32 v86, v97, v86
	v_exp_f32_e32 v69, v69
	v_add_f32_e32 v90, v217, v86
	v_cvt_pk_bf16_f32 v86, v82, v83
	v_cvt_pk_bf16_f32 v82, v101, v91
	v_cvt_pk_bf16_f32 v83, v92, v93
	v_add_f32_e32 v91, 0, v66
	v_exp_f32_e32 v92, v70
	v_add_f32_e32 v91, v67, v91
	v_add_f32_e32 v91, v68, v91
	v_add_f32_e32 v91, v69, v91
	v_add_f32_e32 v70, v92, v91
	v_exp_f32_e32 v91, v71
	v_exp_f32_e32 v93, v72
	v_exp_f32_e32 v73, v73
	v_cvt_pk_bf16_f32 v87, v84, v85
	v_cvt_pk_bf16_f32 v84, v94, v95
	v_exp_f32_e32 v94, v74
	v_add_f32_e32 v70, v91, v70
	v_exp_f32_e32 v75, v75
	v_add_f32_e32 v70, v93, v70
	v_exp_f32_e32 v76, v76
	v_add_f32_e32 v70, v73, v70
	v_exp_f32_e32 v77, v77
	v_add_f32_e32 v70, v94, v70
	v_exp_f32_e32 v78, v78
	v_add_f32_e32 v70, v75, v70
	v_exp_f32_e32 v79, v79
	v_add_f32_e32 v70, v76, v70
	v_exp_f32_e32 v80, v80
	v_add_f32_e32 v70, v77, v70
	v_exp_f32_e32 v81, v81
	v_add_f32_e32 v70, v78, v70
	v_add_f32_e32 v70, v79, v70
	v_add_f32_e32 v70, v80, v70
	v_add_f32_e32 v70, v81, v70
	v_add_f32_e32 v74, v216, v70
	v_cvt_pk_bf16_f32 v70, v66, v67
	v_cvt_pk_bf16_f32 v71, v68, v69
	v_cvt_pk_bf16_f32 v72, v92, v91
	v_cvt_pk_bf16_f32 v73, v93, v73
	v_cvt_pk_bf16_f32 v66, v94, v75
	v_cvt_pk_bf16_f32 v67, v76, v77
	v_cvt_pk_bf16_f32 v68, v78, v79
	ds_read_b128 v[76:79], v32 offset:18432
	ds_read_b128 v[92:95], v32 offset:18464
	s_waitcnt lgkmcnt(1)
	v_mfma_f32_32x32x16_bf16 v[50:65], v[76:79], v[170:173], v[50:65]
	v_cvt_pk_bf16_f32 v88, v99, v98
	v_cvt_pk_bf16_f32 v89, v100, v89
	v_cvt_pk_bf16_f32 v85, v96, v97
	v_cvt_pk_bf16_f32 v69, v80, v81
	s_lshl_b32 s4, s39, 12
	s_add_i32 s40, s40, s4
	s_lshl_b32 s16, s1, 7
	v_mfma_f32_32x32x16_bf16 v[16:31], v[76:79], v[174:177], v[16:31]
	ds_read_b128 v[76:79], v32 offset:23040
	s_add_i32 s0, s0, s78
	s_cmpk_gt_i32 s0, 0x3ff
	s_waitcnt lgkmcnt(0)
	v_mfma_f32_32x32x16_bf16 v[34:49], v[76:79], v[170:173], v[34:49]
	v_mfma_f32_32x32x16_bf16 v[0:15], v[76:79], v[174:177], v[0:15]
	ds_read_b128 v[76:79], v32 offset:23072
	s_waitcnt lgkmcnt(0)
	v_mfma_f32_32x32x16_bf16 v[34:49], v[76:79], v[166:169], v[34:49]
	v_mfma_f32_32x32x16_bf16 v[0:15], v[76:79], v[162:165], v[0:15]
	ds_read_b128 v[76:79], v32 offset:18496
	v_mfma_f32_32x32x16_bf16 v[50:65], v[92:95], v[166:169], v[50:65]
	v_mfma_f32_32x32x16_bf16 v[16:31], v[92:95], v[162:165], v[16:31]
	s_waitcnt lgkmcnt(0)
	v_mfma_f32_32x32x16_bf16 v[50:65], v[76:79], v[86:89], v[50:65]
	v_mfma_f32_32x32x16_bf16 v[16:31], v[76:79], v[70:73], v[16:31]
	ds_read_b128 v[76:79], v32 offset:23104
	s_waitcnt lgkmcnt(0)
	v_mfma_f32_32x32x16_bf16 v[0:15], v[76:79], v[70:73], v[0:15]
	ds_read_b128 v[70:73], v32 offset:18528
	s_waitcnt lgkmcnt(0)
	v_mfma_f32_32x32x16_bf16 v[50:65], v[70:73], v[82:85], v[50:65]
	v_mfma_f32_32x32x16_bf16 v[16:31], v[70:73], v[66:69], v[16:31]
	ds_read_b128 v[70:73], v32 offset:23136
	s_waitcnt lgkmcnt(0)
	s_barrier
	v_mfma_f32_32x32x16_bf16 v[34:49], v[76:79], v[86:89], v[34:49]
	v_mfma_f32_32x32x16_bf16 v[0:15], v[70:73], v[66:69], v[0:15]
	ds_bpermute_b32 v69, v244, v90
	v_or_b32_e32 v68, s40, v202
	v_lshl_add_u64 v[66:67], v[206:207], 0, s[16:17]
	s_waitcnt lgkmcnt(0)
	v_add_f32_e32 v69, v90, v69
	v_mfma_f32_32x32x16_bf16 v[34:49], v[70:73], v[82:85], v[34:49]
	v_div_scale_f32 v70, s[4:5], v69, v69, 1.0
	v_rcp_f32_e32 v71, v70
	s_nop 0
	v_fma_f32 v72, -v70, v71, 1.0
	v_fmac_f32_e32 v71, v72, v71
	v_div_scale_f32 v72, vcc, 1.0, v69, 1.0
	v_mul_f32_e32 v73, v72, v71
	v_fma_f32 v75, -v70, v73, v72
	v_fmac_f32_e32 v73, v75, v71
	v_fma_f32 v70, -v70, v73, v72
	v_div_fmas_f32 v70, v70, v71, v73
	v_div_fixup_f32 v70, v70, v69, 1.0
	v_ashrrev_i32_e32 v69, 31, v68
	v_lshlrev_b64 v[72:73], 11, v[68:69]
	v_pk_mul_f32 v[34:35], v[34:35], v[70:71] op_sel_hi:[1,0]
	v_pk_mul_f32 v[36:37], v[36:37], v[70:71] op_sel_hi:[1,0]
	v_lshl_add_u64 v[72:73], v[66:67], 0, v[72:73]
	v_cvt_pk_bf16_f32 v34, v34, v35
	v_cvt_pk_bf16_f32 v35, v36, v37
	global_store_dwordx2 v[72:73], v[34:35], off offset:64
	v_pk_mul_f32 v[34:35], v[38:39], v[70:71] op_sel_hi:[1,0]
	v_pk_mul_f32 v[36:37], v[40:41], v[70:71] op_sel_hi:[1,0]
	v_cvt_pk_bf16_f32 v34, v34, v35
	v_cvt_pk_bf16_f32 v35, v36, v37
	global_store_dwordx2 v[72:73], v[34:35], off offset:80
	v_pk_mul_f32 v[34:35], v[42:43], v[70:71] op_sel_hi:[1,0]
	v_pk_mul_f32 v[36:37], v[44:45], v[70:71] op_sel_hi:[1,0]
	v_cvt_pk_bf16_f32 v34, v34, v35
	v_cvt_pk_bf16_f32 v35, v36, v37
	global_store_dwordx2 v[72:73], v[34:35], off offset:96
	v_pk_mul_f32 v[34:35], v[46:47], v[70:71] op_sel_hi:[1,0]
	v_pk_mul_f32 v[36:37], v[48:49], v[70:71] op_sel_hi:[1,0]
	v_cvt_pk_bf16_f32 v34, v34, v35
	v_cvt_pk_bf16_f32 v35, v36, v37
	global_store_dwordx2 v[72:73], v[34:35], off offset:112
	ds_bpermute_b32 v34, v244, v74
	v_pk_mul_f32 v[50:51], v[50:51], v[70:71] op_sel_hi:[1,0]
	v_pk_mul_f32 v[52:53], v[52:53], v[70:71] op_sel_hi:[1,0]
	v_cvt_pk_bf16_f32 v50, v50, v51
	v_cvt_pk_bf16_f32 v51, v52, v53
	s_waitcnt lgkmcnt(0)
	v_add_f32_e32 v34, v74, v34
	v_div_scale_f32 v35, s[4:5], v34, v34, 1.0
	v_rcp_f32_e32 v36, v35
	global_store_dwordx2 v[72:73], v[50:51], off
	v_pk_mul_f32 v[50:51], v[54:55], v[70:71] op_sel_hi:[1,0]
	v_pk_mul_f32 v[52:53], v[56:57], v[70:71] op_sel_hi:[1,0]
	v_fma_f32 v37, -v35, v36, 1.0
	v_fmac_f32_e32 v36, v37, v36
	v_div_scale_f32 v37, vcc, 1.0, v34, 1.0
	v_mul_f32_e32 v38, v37, v36
	v_fma_f32 v39, -v35, v38, v37
	v_fmac_f32_e32 v38, v39, v36
	v_fma_f32 v35, -v35, v38, v37
	v_div_fmas_f32 v35, v35, v36, v38
	v_or_b32_e32 v36, 32, v68
	v_div_fixup_f32 v34, v35, v34, 1.0
	v_ashrrev_i32_e32 v37, 31, v36
	v_lshlrev_b64 v[36:37], 11, v[36:37]
	v_pk_mul_f32 v[16:17], v[16:17], v[34:35] op_sel_hi:[1,0]
	v_pk_mul_f32 v[18:19], v[18:19], v[34:35] op_sel_hi:[1,0]
	v_pk_mul_f32 v[0:1], v[0:1], v[34:35] op_sel_hi:[1,0]
	v_pk_mul_f32 v[2:3], v[2:3], v[34:35] op_sel_hi:[1,0]
	v_lshl_add_u64 v[36:37], v[66:67], 0, v[36:37]
	v_cvt_pk_bf16_f32 v16, v16, v17
	v_cvt_pk_bf16_f32 v17, v18, v19
	v_cvt_pk_bf16_f32 v0, v0, v1
	v_cvt_pk_bf16_f32 v1, v2, v3
	global_store_dwordx2 v[36:37], v[16:17], off
	v_pk_mul_f32 v[16:17], v[20:21], v[34:35] op_sel_hi:[1,0]
	v_pk_mul_f32 v[18:19], v[22:23], v[34:35] op_sel_hi:[1,0]
	global_store_dwordx2 v[36:37], v[0:1], off offset:64
	v_pk_mul_f32 v[0:1], v[4:5], v[34:35] op_sel_hi:[1,0]
	v_pk_mul_f32 v[2:3], v[6:7], v[34:35] op_sel_hi:[1,0]
	v_cvt_pk_bf16_f32 v50, v50, v51
	v_cvt_pk_bf16_f32 v51, v52, v53
	v_cvt_pk_bf16_f32 v16, v16, v17
	v_cvt_pk_bf16_f32 v17, v18, v19
	v_cvt_pk_bf16_f32 v0, v0, v1
	v_cvt_pk_bf16_f32 v1, v2, v3
	global_store_dwordx2 v[72:73], v[50:51], off offset:16
	v_pk_mul_f32 v[50:51], v[58:59], v[70:71] op_sel_hi:[1,0]
	v_pk_mul_f32 v[52:53], v[60:61], v[70:71] op_sel_hi:[1,0]
	global_store_dwordx2 v[36:37], v[16:17], off offset:16
	v_pk_mul_f32 v[16:17], v[24:25], v[34:35] op_sel_hi:[1,0]
	v_pk_mul_f32 v[18:19], v[26:27], v[34:35] op_sel_hi:[1,0]
	global_store_dwordx2 v[36:37], v[0:1], off offset:80
	v_pk_mul_f32 v[0:1], v[8:9], v[34:35] op_sel_hi:[1,0]
	v_pk_mul_f32 v[2:3], v[10:11], v[34:35] op_sel_hi:[1,0]
	v_cvt_pk_bf16_f32 v50, v50, v51
	v_cvt_pk_bf16_f32 v51, v52, v53
	v_cvt_pk_bf16_f32 v16, v16, v17
	v_cvt_pk_bf16_f32 v17, v18, v19
	v_cvt_pk_bf16_f32 v0, v0, v1
	v_cvt_pk_bf16_f32 v1, v2, v3
	global_store_dwordx2 v[72:73], v[50:51], off offset:32
	v_pk_mul_f32 v[50:51], v[62:63], v[70:71] op_sel_hi:[1,0]
	v_pk_mul_f32 v[52:53], v[64:65], v[70:71] op_sel_hi:[1,0]
	global_store_dwordx2 v[36:37], v[16:17], off offset:32
	v_pk_mul_f32 v[16:17], v[28:29], v[34:35] op_sel_hi:[1,0]
	v_pk_mul_f32 v[18:19], v[30:31], v[34:35] op_sel_hi:[1,0]
	global_store_dwordx2 v[36:37], v[0:1], off offset:96
	v_pk_mul_f32 v[0:1], v[12:13], v[34:35] op_sel_hi:[1,0]
	v_pk_mul_f32 v[2:3], v[14:15], v[34:35] op_sel_hi:[1,0]
	v_cvt_pk_bf16_f32 v50, v50, v51
	v_cvt_pk_bf16_f32 v51, v52, v53
	v_cvt_pk_bf16_f32 v16, v16, v17
	v_cvt_pk_bf16_f32 v17, v18, v19
	v_cvt_pk_bf16_f32 v0, v0, v1
	v_cvt_pk_bf16_f32 v1, v2, v3
	global_store_dwordx2 v[72:73], v[50:51], off offset:48
	global_store_dwordx2 v[36:37], v[16:17], off offset:48
	global_store_dwordx2 v[36:37], v[0:1], off offset:112
	s_cbranch_scc0 .LBB0_1012
	v_mov_b32_e32 v246, 0x60
	v_mov_b64_e32 v[248:249], 0x300
	v_mov_b64_e32 v[250:251], 0x2ff
